# next-layer filter units moved from PC into the idle workgroups of the FFN-up last tile round (168 instead of 32); hyena spectrum loads prefetched one trip ahead
# speedup vs baseline: 1.0077x; 1.0017x over previous
.LBB0_98:
	s_add_u32 s3, s58, 0x100000
	v_writelane_b32 v250, s3, 3
	s_addc_u32 s3, s59, 0
	s_cmpk_lt_i32 s82, 0x41
	s_cselect_b64 s[4:5], -1, 0
	s_cmp_gt_i32 s82, 64
	v_writelane_b32 v250, s3, 4
	s_cselect_b32 s3, 32, 0
	v_writelane_b32 v250, s4, 5
	s_cmp_ge_i32 s96, s3
	s_mov_b32 s94, 0x3ec3ef15
	v_writelane_b32 v250, s5, 6
	s_cselect_b64 s[4:5], -1, 0
	v_writelane_b32 v250, s4, 7
	s_mov_b32 s74, 0x3f3504f3
	s_mov_b32 s90, -0.5
	v_writelane_b32 v250, s5, 8
	s_sub_i32 s4, s96, s3
	s_lshl_b32 s4, s4, 3
	v_writelane_b32 v250, s4, 9
	s_sub_i32 s4, s82, s3
	s_lshl_b32 s4, s4, 3
	s_add_u32 s13, s58, 0x6e00000
	s_addc_u32 s15, s59, 0
	v_writelane_b32 v250, s4, 10
	s_add_u32 s4, s58, 0x4200000
	v_writelane_b32 v250, s4, 11
	s_addc_u32 s4, s59, 0
	s_add_u32 s18, s58, 0x3a00000
	s_addc_u32 s19, s59, 0
	v_writelane_b32 v250, s4, 12
	s_add_u32 s4, s58, 0x3200000
	v_writelane_b32 v250, s4, 13
	s_addc_u32 s4, s59, 0
	v_writelane_b32 v250, s4, 14
	s_add_u32 s4, s58, 0x3100000
	v_writelane_b32 v250, s4, 15
	s_addc_u32 s4, s59, 0
	s_add_u32 s20, s58, 0x400000
	s_addc_u32 s21, s59, 0
	s_cmp_lt_i32 s96, 32
	v_writelane_b32 v250, s4, 16
	s_cselect_b64 s[4:5], -1, 0
	s_ashr_i32 s97, s96, 31
	v_writelane_b32 v250, s4, 17
	s_add_u32 s8, s58, 0x8400000
	s_addc_u32 s9, s59, 0
	v_writelane_b32 v250, s5, 18
	s_lshl_b64 s[4:5], s[96:97], 18
	s_add_u32 s4, s8, s4
	s_addc_u32 s5, s9, s5
	v_writelane_b32 v250, s4, 19
	s_add_u32 s10, s58, 0x8c00000
	s_addc_u32 s11, s59, 0
	v_writelane_b32 v250, s5, 20
	s_lshl_b64 s[4:5], s[96:97], 17
	s_add_u32 s4, s10, s4
	s_addc_u32 s5, s11, s5
	v_writelane_b32 v250, s4, 21
	v_writelane_b32 v251, s21, 0
	v_mov_b32_e32 v223, 1
	v_writelane_b32 v250, s5, 22
	s_add_u32 s4, s58, 0x300000
	s_addc_u32 s5, s59, 0
	v_writelane_b32 v250, s4, 23
	s_lshl_b32 s24, s96, 6
	s_lshl_b32 s14, s96, 3
	s_lshl_b32 s12, s82, 3
	v_writelane_b32 v250, s5, 24
	s_add_u32 s4, s58, 0xd700000
	s_addc_u32 s5, s59, 0
	s_add_u32 s26, s58, 0x15b00000
	v_writelane_b32 v250, s4, 25
	s_addc_u32 s27, s59, 0
	s_mov_b32 s95, 0x3f6c835e
	v_writelane_b32 v250, s5, 26
	s_add_u32 s4, s58, 0x50300000
	s_addc_u32 s5, s59, 0
	v_writelane_b32 v250, s4, 27
	s_cmp_gt_i32 s96, 31
	s_mov_b32 s75, 0xbf3504f3
	v_writelane_b32 v250, s5, 28
	s_cselect_b64 s[4:5], -1, 0
	v_writelane_b32 v250, s4, 29
	s_mov_b32 s91, 0.5
	v_mov_b32_e32 v229, 0x7f800000
	v_writelane_b32 v250, s5, 30
	s_add_i32 s4, s14, 0xffffff00
	v_writelane_b32 v250, s4, 31
	s_add_i32 s4, s12, 0xffffff00
	v_writelane_b32 v250, s4, 32
	s_add_u32 s4, s58, 0x4200
	s_addc_u32 s5, s59, 0
	v_writelane_b32 v250, s4, 33
	v_mov_b32_e32 v228, 0x41b17218
	v_mov_b32_e32 v230, 0x1e1
	v_writelane_b32 v250, s5, 34
	s_add_u32 s4, s58, 0x4400
	s_addc_u32 s5, s59, 0
	v_writelane_b32 v250, s4, 35
	v_mov_b32_e32 v231, 0x1e0
	v_mov_b64_e32 v[204:205], 0x1ff
	v_writelane_b32 v250, s5, 36
	s_add_u32 s4, s58, 0x4500
	s_addc_u32 s5, s59, 0
	v_writelane_b32 v250, s4, 37
	s_movk_i32 s83, 0x100
	s_movk_i32 s92, 0x6000
	v_writelane_b32 v250, s5, 38
	s_add_u32 s4, s58, 0x4600
	s_addc_u32 s5, s59, 0
	v_writelane_b32 v250, s4, 39
	s_movk_i32 s33, 0x1e00
	s_mov_b32 s86, 0xbfb8aa3b
	v_writelane_b32 v250, s5, 40
	s_add_u32 s4, s58, 0x4700
	s_addc_u32 s5, s59, 0
	v_writelane_b32 v250, s4, 41
	s_movk_i32 s87, 0x90
	s_mov_b32 s60, 0x1ffffffc
	v_writelane_b32 v250, s5, 42
	s_add_u32 s4, s58, 0x4800
	s_addc_u32 s5, s59, 0
	v_writelane_b32 v250, s4, 43
	s_mov_b32 s61, 0x1fffffc
	s_movk_i32 s72, 0x110
	v_writelane_b32 v250, s5, 44
	s_add_u32 s4, s58, 0x4900
	s_addc_u32 s5, s59, 0
	v_writelane_b32 v250, s4, 45
	s_mov_b32 s73, 0x3f317217
	s_movk_i32 s64, 0x1100
	v_writelane_b32 v250, s5, 46
	s_add_u32 s4, s58, 0x4a00
	s_addc_u32 s5, s59, 0
	v_writelane_b32 v250, s4, 47
	s_mov_b32 s81, 0x37500000
	s_mov_b64 s[54:55], 0x1400
	v_writelane_b32 v250, s5, 48
	s_add_u32 s4, s58, 0x4b00
	s_addc_u32 s5, s59, 0
	v_writelane_b32 v250, s4, 49
	s_mov_b64 s[88:89], 0x80
	s_mov_b32 s93, 0xbec3ef15
	v_writelane_b32 v250, s5, 50
	s_add_u32 s4, s58, 0x4c00
	s_addc_u32 s5, s59, 0
	v_writelane_b32 v250, s4, 51
	s_mov_b32 s77, 0xbf6c835e
	s_mov_b64 s[66:67], 0x37500800
	v_writelane_b32 v250, s5, 52
	s_add_u32 s4, s58, 0x4d00
	s_addc_u32 s5, s59, 0
	v_writelane_b32 v250, s4, 53
	s_nop 1
	v_writelane_b32 v250, s5, 54
	s_add_u32 s4, s58, 0x4e00
	s_addc_u32 s5, s59, 0
	v_writelane_b32 v250, s4, 55
	s_nop 1
	v_writelane_b32 v250, s5, 56
	s_add_u32 s4, s58, 0x4f00
	s_addc_u32 s5, s59, 0
	v_writelane_b32 v250, s4, 57
	s_nop 1
	v_writelane_b32 v250, s5, 58
	s_add_u32 s4, s58, 0x5000
	s_addc_u32 s5, s59, 0
	v_writelane_b32 v250, s4, 59
	s_nop 1
	v_writelane_b32 v250, s5, 60
	s_add_u32 s4, s58, 0x5100
	s_addc_u32 s5, s59, 0
	v_writelane_b32 v250, s4, 61
	s_nop 1
	v_writelane_b32 v250, s5, 62
	s_add_u32 s4, s58, 0x5200
	s_addc_u32 s5, s59, 0
	v_writelane_b32 v250, s4, 63
	s_nop 1
	v_writelane_b32 v252, s5, 0
	s_add_u32 s4, s58, 0x5300
	s_addc_u32 s5, s59, 0
	v_writelane_b32 v252, s4, 1
	s_cmp_eq_u32 s2, 15
	s_nop 0
	v_writelane_b32 v252, s5, 2
	s_cselect_b64 s[4:5], -1, 0
	v_writelane_b32 v252, s4, 3
	s_cmp_eq_u32 s2, 14
	s_nop 0
	v_writelane_b32 v252, s5, 4
	s_cselect_b64 s[4:5], -1, 0
	v_writelane_b32 v252, s4, 5
	s_cmp_eq_u32 s2, 13
	s_nop 0
	v_writelane_b32 v252, s5, 6
	s_cselect_b64 s[4:5], -1, 0
	v_writelane_b32 v252, s4, 7
	s_cmp_eq_u32 s2, 12
	s_nop 0
	v_writelane_b32 v252, s5, 8
	s_cselect_b64 s[4:5], -1, 0
	v_writelane_b32 v252, s4, 9
	s_cmp_eq_u32 s2, 11
	s_nop 0
	v_writelane_b32 v252, s5, 10
	s_cselect_b64 s[4:5], -1, 0
	v_writelane_b32 v252, s4, 11
	s_cmp_eq_u32 s2, 10
	s_nop 0
	v_writelane_b32 v252, s5, 12
	s_cselect_b64 s[4:5], -1, 0
	v_writelane_b32 v252, s4, 13
	s_cmp_eq_u32 s2, 9
	s_nop 0
	v_writelane_b32 v252, s5, 14
	s_cselect_b64 s[4:5], -1, 0
	v_writelane_b32 v252, s4, 15
	s_cmp_eq_u32 s2, 8
	s_nop 0
	v_writelane_b32 v252, s5, 16
	s_cselect_b64 s[4:5], -1, 0
	v_writelane_b32 v252, s4, 17
	s_cmp_eq_u32 s2, 7
	s_nop 0
	v_writelane_b32 v252, s5, 18
	s_cselect_b64 s[4:5], -1, 0
	v_writelane_b32 v252, s4, 19
	s_cmp_eq_u32 s2, 6
	s_nop 0
	v_writelane_b32 v252, s5, 20
	s_cselect_b64 s[4:5], -1, 0
	v_writelane_b32 v252, s4, 21
	s_cmp_eq_u32 s2, 5
	s_nop 0
	v_writelane_b32 v252, s5, 22
	s_cselect_b64 s[4:5], -1, 0
	v_writelane_b32 v252, s4, 23
	s_cmp_eq_u32 s2, 4
	s_nop 0
	v_writelane_b32 v252, s5, 24
	s_cselect_b64 s[4:5], -1, 0
	v_writelane_b32 v252, s4, 25
	s_cmp_eq_u32 s2, 3
	s_nop 0
	v_writelane_b32 v252, s5, 26
	s_cselect_b64 s[4:5], -1, 0
	v_writelane_b32 v252, s4, 27
	s_cmp_eq_u32 s2, 2
	s_nop 0
	v_writelane_b32 v252, s5, 28
	s_cselect_b64 s[4:5], -1, 0
	v_writelane_b32 v252, s4, 29
	s_cmp_eq_u32 s2, 1
	s_nop 0
	v_writelane_b32 v252, s5, 30
	s_cselect_b64 s[4:5], -1, 0
	v_writelane_b32 v252, s4, 31
	s_cmp_eq_u32 s2, 0
	s_nop 0
	v_writelane_b32 v252, s5, 32
	s_cselect_b64 s[4:5], -1, 0
	s_lshl_b32 s2, s2, 8
	v_writelane_b32 v252, s4, 33
	s_add_u32 s2, s16, s2
	s_nop 0
	v_writelane_b32 v252, s5, 34
	s_addc_u32 s4, s17, 0
	s_add_u32 s6, s2, 0x1400
	s_addc_u32 s7, s4, 0
	v_writelane_b32 v252, s6, 35
	s_nop 1
	v_writelane_b32 v252, s7, 36
	s_add_u32 s6, s2, 0x2400
	s_addc_u32 s7, s4, 0
	v_writelane_b32 v252, s6, 37
	s_add_u32 s4, s58, 0x7400
	s_addc_u32 s5, s59, 0
	v_writelane_b32 v252, s7, 38
	v_writelane_b32 v252, s4, 39
	s_nop 1
	v_writelane_b32 v252, s5, 40
	s_add_u32 s4, s58, 0x7500
	s_addc_u32 s5, s59, 0
	s_add_u32 s22, s58, 0x19d00000
	s_addc_u32 s23, s59, 0
	s_add_u32 s16, s58, 0x31100000
	v_writelane_b32 v252, s4, 41
	s_addc_u32 s17, s59, 0
	s_nop 0
	v_writelane_b32 v252, s5, 42
	s_add_u32 s4, s58, 0x4c000000
	s_addc_u32 s5, s59, 0
	v_writelane_b32 v252, s4, 43
	s_add_u32 s2, s58, 0x53800000
	s_nop 0
	v_writelane_b32 v252, s5, 44
	v_writelane_b32 v252, s2, 45
	s_addc_u32 s2, s59, 0
	s_cmpk_lt_i32 s96, 0xb9a
	v_writelane_b32 v252, s2, 46
	s_cselect_b64 s[4:5], -1, 0
	s_lshr_b32 s2, s97, 29
	s_add_i32 s2, s96, s2
	s_ashr_i32 s25, s2, 3
	s_and_b32 s2, s2, -8
	v_writelane_b32 v252, s4, 47
	s_sub_i32 s28, s96, s2
	s_ashr_i32 s2, s82, 31
	v_writelane_b32 v252, s5, 48
	s_mul_i32 s4, s28, 0x173
	s_add_i32 s4, s4, 2
	s_cmpk_eq_i32 s82, 0x100
	v_writelane_b32 v252, s2, 49
	s_cselect_b64 s[6:7], -1, 0
	v_writelane_b32 v252, s6, 50
	s_cmpk_lg_i32 s82, 0x100
	s_nop 0
	v_writelane_b32 v252, s7, 51
	s_cselect_b64 s[6:7], -1, 0
	v_writelane_b32 v252, s6, 52
	s_add_u32 s2, s58, 0xa000
	s_nop 0
	v_writelane_b32 v252, s7, 53
	v_writelane_b32 v252, s2, 54
	s_addc_u32 s2, s59, 0
	s_cmpk_lt_i32 s96, 0xa0
	v_writelane_b32 v252, s2, 55
	s_cselect_b64 s[6:7], -1, 0
	v_writelane_b32 v252, s6, 56
	s_cmpk_gt_i32 s96, 0x9f
	s_nop 0
	v_writelane_b32 v252, s7, 57
	s_cselect_b64 s[6:7], -1, 0
	v_writelane_b32 v252, s6, 58
	s_nop 1
	v_writelane_b32 v252, s7, 59
	s_add_u32 s6, s58, 0x2dd00000
	s_addc_u32 s7, s59, 0
	v_writelane_b32 v252, s6, 60
	s_nop 1
	v_writelane_b32 v252, s7, 61
	s_add_u32 s6, s58, 0x33900000
	s_addc_u32 s7, s59, 0
	v_writelane_b32 v252, s6, 62
	s_ashr_i32 s30, s96, 5
	s_ashr_i32 s31, s30, 31
	v_writelane_b32 v252, s7, 63
	s_mov_b32 s6, s30
	s_and_b32 s29, s96, 31
	v_writelane_b32 v253, s6, 0
	s_lshl_b32 s2, s29, 10
	s_nop 0
	v_writelane_b32 v253, s7, 1
	s_lshl_b64 s[6:7], s[30:31], 23
	s_add_u32 s5, s16, s6
	v_writelane_b32 v253, s16, 2
	s_addc_u32 s6, s17, s7
	s_nop 0
	v_writelane_b32 v253, s17, 3
	s_add_u32 s16, s5, s2
	s_addc_u32 s17, s6, 0
	s_lshl_b32 s2, s29, 17
	s_add_u32 s6, s10, s2
	s_addc_u32 s7, s11, 0
	v_writelane_b32 v253, s10, 4
	s_add_u32 s10, s6, 0x10000
	v_writelane_b32 v253, s11, 5
	s_addc_u32 s11, s7, 0
	v_writelane_b32 v253, s10, 6
	s_nop 1
	v_writelane_b32 v253, s11, 7
	s_add_u32 s10, s16, 0x400000
	v_writelane_b32 v253, s16, 8
	s_addc_u32 s11, s17, 0
	s_nop 0
	v_writelane_b32 v253, s17, 9
	v_writelane_b32 v253, s10, 10
	s_nop 1
	v_writelane_b32 v253, s11, 11
	s_add_u32 s10, s6, 0x10080
	v_writelane_b32 v253, s6, 12
	s_addc_u32 s11, s7, 0
	s_add_u32 s2, s58, 0x8000
	v_writelane_b32 v253, s7, 13
	v_writelane_b32 v253, s10, 14
	s_nop 1
	v_writelane_b32 v253, s11, 15
	v_writelane_b32 v253, s2, 16
	s_addc_u32 s2, s59, 0
	s_add_u32 s16, s58, 0x3f900000
	s_addc_u32 s17, s59, 0
	s_add_u32 s6, s58, 0x4bf00000
	v_writelane_b32 v253, s2, 17
	s_addc_u32 s7, s59, 0
	v_writelane_b32 v253, s6, 18
	s_lshl_b32 s2, s96, 5
	s_nop 0
	v_writelane_b32 v253, s7, 19
	v_writelane_b32 v253, s2, 20
	s_lshl_b32 s2, s82, 5
	s_add_u32 s6, s58, 0x43b00000
	v_writelane_b32 v253, s2, 21
	s_addc_u32 s7, s59, 0
	s_mul_i32 s2, s96, 0x1c0
	v_writelane_b32 v253, s6, 22
	s_sub_i32 s2, s2, 64
	s_nop 0
	v_writelane_b32 v253, s7, 23
	s_add_u32 s6, s58, 0x36100000
	v_writelane_b32 v253, s2, 24
	s_addc_u32 s7, s59, 0
	v_writelane_b32 v253, s6, 25
	s_lshl_b32 s2, s29, 18
	s_nop 0
	v_writelane_b32 v253, s7, 26
	s_add_u32 s6, s8, s2
	v_writelane_b32 v253, s29, 27
	s_addc_u32 s7, s9, 0
	v_writelane_b32 v253, s8, 28
	s_add_u32 s8, s6, 0x20000
	v_writelane_b32 v253, s9, 29
	s_addc_u32 s9, s7, 0
	v_writelane_b32 v253, s8, 30
	s_nop 1
	v_writelane_b32 v253, s9, 31
	s_add_u32 s8, s6, 0x20080
	v_writelane_b32 v253, s6, 32
	s_addc_u32 s9, s7, 0
	s_nop 0
	v_writelane_b32 v253, s7, 33
	v_writelane_b32 v253, s8, 34
	s_add_u32 s6, s58, 0x4f200000
	s_addc_u32 s7, s59, 0
	v_writelane_b32 v253, s9, 35
	v_writelane_b32 v253, s6, 36
	s_add_u32 s2, s58, 0x47d00000
	s_nop 0
	v_writelane_b32 v253, s7, 37
	v_writelane_b32 v253, s2, 38
	s_addc_u32 s2, s59, 0
	s_add_u32 s6, s58, 0x37500000
	v_writelane_b32 v253, s2, 39
	s_addc_u32 s7, s59, 0
	s_add_i32 s2, s82, 0x107
	v_writelane_b32 v253, s6, 40
	s_cmpk_lt_i32 s96, 0x84
	s_nop 0
	v_writelane_b32 v253, s7, 41
	s_cselect_b64 s[6:7], -1, 0
	v_writelane_b32 v253, s6, 42
	s_cmp_lt_i32 s96, 16
	s_nop 0
	v_writelane_b32 v253, s7, 43
	s_cselect_b64 s[6:7], -1, 0
	v_writelane_b32 v253, s6, 44
	s_cmp_gt_i32 s96, 15
	s_nop 0
	v_writelane_b32 v253, s7, 45
	s_cselect_b64 s[6:7], -1, 0
	s_add_i32 s5, s96, 0xf8
	v_writelane_b32 v253, s6, 46
	s_add_u32 s30, s58, 0x3b700000
	s_addc_u32 s31, s59, 0
	v_writelane_b32 v253, s7, 47
	v_writelane_b32 v253, s5, 48
	s_add_u32 s5, s58, 0x9000
	v_writelane_b32 v253, s5, 49
	s_addc_u32 s5, s59, 0
	s_cmpk_lt_i32 s96, 0x200
	v_writelane_b32 v253, s5, 50
	s_cselect_b64 s[6:7], -1, 0
	s_lshl_b32 s10, s28, 6
	v_writelane_b32 v253, s6, 51
	s_cmp_lt_i32 s96, 64
	s_nop 0
	v_writelane_b32 v253, s7, 52
	s_cselect_b64 s[6:7], -1, 0
	s_lshr_b32 s5, s97, 30
	v_writelane_b32 v253, s6, 53
	s_add_i32 s5, s96, s5
	s_nop 0
	v_writelane_b32 v253, s7, 54
	s_and_b32 s6, s5, -4
	s_sub_i32 s6, s96, s6
	s_ashr_i32 s7, s5, 5
	s_bfe_u32 s5, s5, 0x30002
	s_lshl_b32 s8, s6, 8
	s_or_b32 s8, s8, s5
	s_add_i32 s34, s7, 64
	v_writelane_b32 v253, s8, 55
	s_mov_b32 s8, s34
	s_ashr_i32 s35, s34, 31
	v_writelane_b32 v253, s8, 56
	s_nop 1
	v_writelane_b32 v253, s9, 57
	s_lshl_b64 s[8:9], s[34:35], 20
	s_add_u32 s8, s30, s8
	s_addc_u32 s9, s31, s9
	s_ashr_i32 s7, s6, 31
	s_lshl_b64 s[6:7], s[6:7], 10
	s_add_u32 s34, s8, s6
	s_addc_u32 s35, s9, s7
	s_lshl_b32 s5, s5, 20
	s_add_u32 s5, s18, s5
	s_addc_u32 s8, s19, 0
	s_add_u32 s6, s5, s6
	s_addc_u32 s7, s8, s7
	s_add_u32 s8, s6, 0x80000
	s_addc_u32 s9, s7, 0
	v_writelane_b32 v253, s8, 58
	s_nop 1
	v_writelane_b32 v253, s9, 59
	s_add_u32 s8, s34, 0x80000
	v_writelane_b32 v253, s34, 60
	s_addc_u32 s9, s35, 0
	s_nop 0
	v_writelane_b32 v253, s35, 61
	v_writelane_b32 v253, s8, 62
	s_nop 1
	v_writelane_b32 v253, s9, 63
	s_add_u32 s8, s6, 0x80080
	v_writelane_b32 v254, s6, 0
	s_addc_u32 s9, s7, 0
	s_nop 0
	v_writelane_b32 v254, s7, 1
	v_writelane_b32 v254, s8, 2
	s_add_u32 s6, s58, 0x52f00000
	s_addc_u32 s7, s59, 0
	v_writelane_b32 v254, s9, 3
	v_writelane_b32 v254, s6, 4
	s_cmpk_gt_i32 s96, 0x57
	s_nop 0
	v_writelane_b32 v254, s7, 5
	s_cselect_b64 s[6:7], -1, 0
	v_writelane_b32 v254, s6, 6
	s_lshl_b32 s5, s96, 9
	s_lshl_b32 s29, s82, 9
	v_writelane_b32 v254, s7, 7
	s_cmpk_lt_i32 s96, 0xb0
	v_writelane_b32 v254, s5, 8
	s_cselect_b64 s[6:7], -1, 0
	s_mul_hi_i32 s5, s96, 0x2e8ba2e9
	v_writelane_b32 v254, s6, 9
	s_nop 1
	v_writelane_b32 v254, s7, 10
	s_lshr_b32 s6, s5, 31
	s_ashr_i32 s5, s5, 1
	s_add_i32 s5, s5, s6
	s_ashr_i32 s6, s5, 3
	s_add_i32 s9, s6, 64
	s_mul_i32 s6, s5, 11
	s_sub_i32 s6, s96, s6
	s_and_b32 s5, s5, 7
	s_lshl_b32 s7, s6, 8
	s_or_b32 s7, s7, s5
	v_writelane_b32 v254, s7, 11
	s_mul_i32 s7, s9, 0x2c0000
	s_add_u32 s8, s16, s7
	s_mul_hi_i32 s7, s9, 0x2c0000
	v_writelane_b32 v254, s9, 12
	s_addc_u32 s9, s17, s7
	s_ashr_i32 s7, s6, 31
	s_lshl_b64 s[6:7], s[6:7], 10
	s_add_u32 s34, s8, s6
	s_addc_u32 s35, s9, s7
	s_mul_i32 s5, s5, 0x2c0000
	s_add_u32 s5, s13, s5
	s_addc_u32 s8, s15, 0
	s_add_u32 s6, s5, s6
	s_addc_u32 s7, s8, s7
	s_add_u32 s8, s6, 0x160000
	s_addc_u32 s9, s7, 0
	v_writelane_b32 v254, s8, 13
	s_mul_i32 s5, s28, 0x174
	s_nop 0
	v_writelane_b32 v254, s9, 14
	s_add_u32 s8, s34, 0x160000
	v_writelane_b32 v254, s34, 15
	s_addc_u32 s9, s35, 0
	s_nop 0
	v_writelane_b32 v254, s35, 16
	v_writelane_b32 v254, s8, 17
	s_nop 1
	v_writelane_b32 v254, s9, 18
	s_add_u32 s8, s6, 0x160080
	v_writelane_b32 v254, s6, 19
	s_addc_u32 s9, s7, 0
	s_cmp_lt_i32 s28, 2
	s_cselect_b32 s4, s5, s4
	s_add_i32 s4, s4, s25
	s_mul_hi_i32 s5, s4, 0xb60b60b7
	s_add_i32 s5, s5, s4
	v_writelane_b32 v254, s7, 20
	s_lshr_b32 s6, s5, 31
	s_ashr_i32 s5, s5, 7
	v_writelane_b32 v254, s8, 21
	s_add_i32 s5, s5, s6
	s_mul_i32 s6, s5, 0xb4
	v_writelane_b32 v254, s9, 22
	s_lshl_b32 s9, s5, 2
	s_sub_i32 s8, s4, s6
	s_sub_i32 s4, 0x42, s9
	s_min_u32 s11, s4, 4
	s_cmp_lt_i32 s28, 0
	s_cselect_b64 s[4:5], -1, 0
	v_writelane_b32 v254, s4, 23
	v_cvt_f32_ubyte0_e32 v2, s11
	v_cvt_f32_i32_e32 v1, s8
	v_writelane_b32 v254, s5, 24
	s_and_b64 s[4:5], s[4:5], exec
	s_mul_i32 s4, s28, 0x41
	s_cselect_b32 s4, s4, s10
	s_add_i32 s4, s4, s25
	s_ashr_i32 s5, s4, 31
	s_lshr_b32 s5, s5, 27
	s_add_i32 s5, s4, s5
	s_and_b32 s6, s5, 0xffe0
	s_sub_i32 s4, s4, s6
	s_bfe_i32 s6, s4, 0x80000
	s_bfe_u32 s6, s6, 0x2000d
	s_add_i32 s6, s4, s6
	s_and_b32 s7, s6, 0xfc
	s_sub_i32 s4, s4, s7
	s_ashr_i32 s5, s5, 5
	s_lshl_b32 s5, s5, 2
	s_sext_i32_i8 s4, s4
	s_bfe_i32 s6, s6, 0x80000
	s_add_i32 s34, s5, s4
	s_sext_i32_i16 s6, s6
	s_ashr_i32 s35, s34, 31
	s_ashr_i32 s10, s6, 2
	s_lshr_b32 s4, s6, 2
	s_lshl_b64 s[6:7], s[34:35], 20
	v_writelane_b32 v254, s25, 25
	s_add_u32 s6, s30, s6
	v_writelane_b32 v254, s30, 26
	s_addc_u32 s7, s31, s7
	s_bfe_i64 s[4:5], s[4:5], 0x100000
	s_lshl_b64 s[4:5], s[4:5], 20
	s_add_u32 s4, s18, s4
	v_writelane_b32 v254, s31, 27
	s_addc_u32 s5, s19, s5
	v_writelane_b32 v254, s18, 28
	s_add_u32 s18, s4, 0x80000
	v_writelane_b32 v254, s19, 29
	s_addc_u32 s19, s5, 0
	v_writelane_b32 v254, s18, 30
	v_rcp_iflag_f32_e32 v3, v2
	s_mov_b32 s25, 0x7f800000
	v_writelane_b32 v254, s19, 31
	s_add_u32 s18, s6, 0x80000
	v_writelane_b32 v254, s6, 32
	s_addc_u32 s19, s7, 0
	v_mul_f32_e32 v3, v1, v3
	v_writelane_b32 v254, s7, 33
	v_writelane_b32 v254, s18, 34
	s_add_u32 s6, s4, 0x80080
	v_trunc_f32_e32 v3, v3
	v_writelane_b32 v254, s19, 35
	v_writelane_b32 v254, s4, 36
	s_addc_u32 s7, s5, 0
	v_fma_f32 v1, -v3, v2, v1
	v_writelane_b32 v254, s5, 37
	v_writelane_b32 v254, s6, 38
	s_mul_i32 s5, s34, 0x2c0000
	s_mul_hi_i32 s4, s34, 0x2c0000
	v_writelane_b32 v254, s7, 39
	s_mov_b32 s6, s34
	v_writelane_b32 v254, s6, 40
	s_nop 1
	v_writelane_b32 v254, s7, 41
	s_add_u32 s6, s16, s5
	v_writelane_b32 v254, s16, 42
	s_addc_u32 s7, s17, s4
	s_mul_i32 s5, s10, 0x2c0000
	v_writelane_b32 v254, s17, 43
	s_mul_hi_i32 s4, s10, 0x2c0000
	s_add_u32 s16, s13, s5
	v_writelane_b32 v254, s10, 44
	s_addc_u32 s17, s15, s4
	v_writelane_b32 v254, s13, 45
	s_add_u32 s4, s16, 0x160000
	v_writelane_b32 v254, s15, 46
	s_addc_u32 s5, s17, 0
	v_writelane_b32 v254, s4, 47
	s_nop 1
	v_writelane_b32 v254, s5, 48
	s_add_u32 s4, s6, 0x160000
	v_writelane_b32 v254, s6, 49
	s_addc_u32 s5, s7, 0
	s_nop 0
	v_writelane_b32 v254, s7, 50
	v_writelane_b32 v254, s4, 51
	s_nop 1
	v_writelane_b32 v254, s5, 52
	s_add_u32 s4, s16, 0x160080
	v_writelane_b32 v254, s16, 53
	s_addc_u32 s5, s17, 0
	s_nop 0
	v_writelane_b32 v254, s17, 54
	v_writelane_b32 v254, s4, 55
	s_nop 1
	v_writelane_b32 v254, s5, 56
	s_ashr_i32 s4, s8, 30
	s_or_b32 s6, s4, 1
	v_writelane_b32 v254, s28, 57
	s_lshr_b32 s4, s28, 31
	v_writelane_b32 v254, s4, 58
	v_cmp_ge_f32_e64 s[4:5], |v1|, v2
	v_cvt_i32_f32_e32 v1, v3
	s_and_b64 s[4:5], s[4:5], exec
	s_cselect_b32 s4, s6, 0
	v_mbcnt_lo_u32_b32 v2, -1, 0
	v_readfirstlane_b32 s5, v1
	s_add_i32 s4, s5, s4
	s_mul_i32 s5, s4, s11
	s_sub_i32 s5, s8, s5
	s_sext_i32_i16 s5, s5
	s_add_i32 s8, s9, s5
	s_mov_b32 s6, s8
	s_ashr_i32 s9, s8, 31
	v_writelane_b32 v254, s6, 59
	v_mov_b32_e32 v3, 0
	v_mbcnt_hi_u32_b32 v222, -1, v2
	v_writelane_b32 v254, s7, 60
	s_lshl_b64 s[6:7], s[8:9], 20
	s_add_u32 s6, s26, s6
	v_writelane_b32 v254, s26, 61
	s_addc_u32 s7, s27, s7
	s_sext_i32_i16 s8, s4
	s_bfe_i64 s[4:5], s[4:5], 0x100000
	s_lshl_b64 s[4:5], s[4:5], 20
	s_add_u32 s4, s20, s4
	s_addc_u32 s5, s21, s5
	v_writelane_b32 v251, s8, 1
	s_add_i32 s8, s8, -14
	s_cmp_lt_u32 s8, 6
	s_cselect_b32 s9, s5, s7
	s_cselect_b32 s8, s4, s6
	v_writelane_b32 v251, s8, 2
	s_cselect_b32 s5, s7, s5
	s_cselect_b32 s4, s6, s4
	v_writelane_b32 v251, s9, 3
	v_writelane_b32 v251, s4, 4
	v_writelane_b32 v254, s27, 62
	v_writelane_b32 v254, s20, 63
	v_writelane_b32 v251, s5, 5
	s_abs_i32 s4, s82
	v_cvt_f32_u32_e32 v1, s4
	s_sub_i32 s5, 0, s4
	s_mov_b32 s21, 0x70007
	s_movk_i32 s20, 0x1000
	v_rcp_iflag_f32_e32 v1, v1
	s_mov_b32 s28, 0x800000
	v_mul_f32_e32 v1, 0x4f7ffffe, v1
	v_cvt_u32_f32_e32 v1, v1
	s_nop 0
	v_readfirstlane_b32 s6, v1
	s_mul_i32 s5, s5, s6
	s_mul_hi_u32 s5, s6, s5
	s_add_i32 s6, s6, s5
	s_abs_i32 s5, s2
	s_mul_hi_u32 s6, s5, s6
	s_mul_i32 s7, s6, s4
	s_sub_i32 s5, s5, s7
	s_xor_b32 s2, s2, s82
	s_ashr_i32 s2, s2, 31
	s_add_i32 s7, s6, 1
	s_sub_i32 s8, s5, s4
	s_cmp_ge_u32 s5, s4
	s_cselect_b32 s6, s7, s6
	s_cselect_b32 s5, s8, s5
	s_add_i32 s7, s6, 1
	s_cmp_ge_u32 s5, s4
	s_cselect_b32 s4, s7, s6
	s_xor_b32 s4, s4, s2
	s_sub_i32 s2, s4, s2
	v_writelane_b32 v251, s2, 6
	s_lshl_b32 s2, s3, 6
	s_lshl_b32 s4, s82, 6
	s_sub_i32 s4, s4, s2
	v_writelane_b32 v251, s4, 7
	v_writelane_b32 v251, s24, 8
	s_sub_i32 s2, s24, s2
	v_writelane_b32 v251, s2, 9
	s_lshl_b32 s2, s3, 3
	s_sub_i32 s2, s14, s2
	s_addk_i32 s2, 0xcb40
	v_writelane_b32 v251, s2, 10
	s_lshl_b32 s2, s3, 9
	v_writelane_b32 v251, s29, 11
	s_sub_i32 s2, s29, s2
	v_writelane_b32 v251, s2, 12
	s_add_i32 s2, s14, 0xffffc000
	v_writelane_b32 v251, s2, 13
	s_add_i32 s2, s14, 0xffffbf00
	v_writelane_b32 v251, s2, 14
	s_add_i32 s2, s96, 0xffffff7c
	v_writelane_b32 v251, s2, 15
	v_writelane_b32 v251, s14, 16
	s_ashr_i32 s2, s14, 31
	v_writelane_b32 v251, s2, 17
	s_add_i32 s2, 0, 0x8400
	v_writelane_b32 v251, s2, 18
	s_add_i32 s2, 0, 0x4400
	v_writelane_b32 v251, s2, 19
	s_add_i32 s2, 0, 0x22040
	v_writelane_b32 v251, s2, 20
	s_add_i32 s2, 0, 0x1ea00
	v_writelane_b32 v251, s2, 21
	v_cmp_eq_u32_e64 s[4:5], 0, v0
	s_ashr_i32 s13, s12, 31
	s_movk_i32 s24, 0x880
	v_writelane_b32 v251, s4, 22
	v_mov_b32_e32 v1, 0x358637bd
	s_movk_i32 s2, 0x480
	v_writelane_b32 v251, s5, 23
	s_lshl_b64 s[4:5], s[12:13], 13
	v_writelane_b32 v251, s4, 24
	s_add_i32 s3, 0, 0x1a600
	s_add_i32 s65, 0, 0x16200
	v_writelane_b32 v251, s5, 25
	s_mov_b32 s4, s12
	v_writelane_b32 v251, s4, 26
	s_add_i32 s80, 0, 0x11c00
	s_mov_b32 s8, 0
	v_writelane_b32 v251, s5, 27
	s_lshl_b64 s[4:5], s[12:13], 12
	v_writelane_b32 v251, s4, 28
	s_nop 1
	v_writelane_b32 v251, s5, 29
	s_mov_b64 s[4:5], 0
	v_writelane_b32 v251, s4, 30
	s_nop 1
	v_writelane_b32 v251, s5, 31
	s_mov_b64 s[4:5], 0x2100
	v_writelane_b32 v251, s4, 32
	s_nop 1
	v_writelane_b32 v251, s5, 33
	s_mov_b32 s5, 0
	v_writelane_b32 v251, s4, 34
	s_nop 1
	v_writelane_b32 v251, s5, 35
	v_writelane_b32 v251, s96, 36
	s_nop 1
	v_writelane_b32 v251, s97, 37
	s_branch .LBB0_102

.LBB0_891:
	v_readlane_b32 s4, v251, 34
	v_readlane_b32 s5, v251, 35
	v_readlane_b32 s12, v251, 39
	s_mov_b32 s7, s5
	v_readlane_b32 s13, v251, 40
	s_lshl_b32 s6, s12, 7
	v_writelane_b32 v251, s4, 34
	v_readlane_b32 s10, v252, 50
	v_readlane_b32 s11, v252, 51
	v_writelane_b32 v251, s5, 35
	s_lshl_b64 s[4:5], s[6:7], 2
	v_readlane_b32 s6, v253, 16
	s_add_u32 s18, s6, s4
	v_readlane_b32 s4, v253, 17
	s_addc_u32 s19, s4, s5
	s_cmp_lg_u32 s12, 0
	s_cselect_b64 s[4:5], -1, 0
	s_and_b64 s[6:7], s[4:5], s[10:11]
	s_and_b64 s[4:5], s[6:7], exec
	s_cselect_b32 s4, 0x178, 0
	s_cmp_eq_u32 s12, 0
	s_cselect_b64 s[8:9], -1, 0
	s_and_b64 s[8:9], s[8:9], s[10:11]
	s_and_b64 s[8:9], s[8:9], exec
	s_movk_i32 s5, 0x1a0
	s_cselect_b32 s5, s5, 0x200
	s_and_b64 s[6:7], s[6:7], exec
	s_cselect_b32 s5, 8, s5
	s_cselect_b32 s7, 0, 0x200
	s_add_i32 s6, s5, 0x210
	s_lshl_b64 s[8:9], s[12:13], 13
	s_add_i32 s7, s6, s7
	v_writelane_b32 v251, s8, 43
	s_bitcmp0_b32 s12, 0
	s_nop 0
	v_writelane_b32 v251, s9, 44
	s_mov_b32 s8, 0x9300000
	s_cselect_b32 s8, s8, 0x21900000
	s_lshl_b64 s[44:45], s[12:13], 1
	s_lshl_b64 s[46:47], s[12:13], 5
	s_lshl_b64 s[48:49], s[12:13], 19
	s_add_u32 s8, s58, s8
	s_addc_u32 s9, s59, 0
	s_branch .LBB0_895

.LBB0_1455:
	v_readlane_b32 s10, v255, 1
	s_lshl_b32 s7, s52, 1
	v_readlane_b32 s11, v255, 2
	s_and_b64 s[10:11], s[10:11], exec
	s_cselect_b32 s10, 0, 0x4002000
	s_or_b32 s29, s52, 1
	v_cmp_ge_i32_e64 s[14:15], s52, v59
	s_sub_i32 s49, 32, s50
	s_add_i32 s8, s7, -1
	v_readlane_b32 s11, v251, 53
	s_add_u32 s31, s11, s10
	v_readlane_b32 s10, v251, 54
	v_writelane_b32 v255, s14, 1
	s_addc_u32 s78, s10, 0
	v_lshlrev_b32_e32 v158, 1, v59
	v_writelane_b32 v255, s15, 2
	s_and_saveexec_b64 s[16:17], s[14:15]
	s_cbranch_execz .LBB0_1464
	v_readlane_b32 s10, v251, 62
	s_mul_i32 s10, s29, s10
	s_lshl_b32 s10, s10, 4
	s_add_u32 s26, s31, s10
	s_addc_u32 s27, s78, 0
	v_lshlrev_b32_e32 v2, 1, v59
	s_mov_b64 s[34:35], 0
	v_mov_b32_e32 v97, v59
	v_mov_b32_e32 v236, v97
	v_min_i32_e32 v236, s52, v236
	v_ashrrev_i32_e32 v237, 31, v236
	v_lshl_add_u64 v[236:237], v[236:237], 4, s[26:27]
	v_add_u32_e32 v238, 0x200, v97
	v_min_i32_e32 v238, s52, v238
	v_ashrrev_i32_e32 v239, 31, v238
	v_lshl_add_u64 v[238:239], v[238:239], 4, s[26:27]
	v_add_u32_e32 v240, 0x400, v97
	v_min_i32_e32 v240, s52, v240
	v_ashrrev_i32_e32 v241, 31, v240
	v_lshl_add_u64 v[240:241], v[240:241], 4, s[26:27]
	v_add_u32_e32 v242, 0x600, v97
	v_min_i32_e32 v242, s52, v242
	v_ashrrev_i32_e32 v243, 31, v242
	v_lshl_add_u64 v[242:243], v[242:243], 4, s[26:27]
	global_load_dwordx4 v[214:217], v[236:237], off
	global_load_dwordx4 v[218:221], v[238:239], off
	global_load_dwordx4 v[224:227], v[240:241], off
	global_load_dwordx4 v[232:235], v[242:243], off
	s_branch .LBB0_1458

.LBB0_1458:
	v_add_u32_e32 v111, 0x200, v97
	v_add_u32_e32 v109, 0x400, v97
	v_add_u32_e32 v99, 0x600, v97
	s_waitcnt vmcnt(0)
	v_mov_b64_e32 v[116:117], v[214:215]
	v_mov_b64_e32 v[118:119], v[216:217]
	v_mov_b64_e32 v[44:45], v[218:219]
	v_mov_b64_e32 v[46:47], v[220:221]
	v_mov_b64_e32 v[40:41], v[224:225]
	v_mov_b64_e32 v[42:43], v[226:227]
	v_mov_b64_e32 v[36:37], v[232:233]
	v_mov_b64_e32 v[38:39], v[234:235]
	v_add_u32_e32 v236, 0x800, v97
	v_min_i32_e32 v236, s52, v236
	v_ashrrev_i32_e32 v237, 31, v236
	v_lshl_add_u64 v[236:237], v[236:237], 4, s[26:27]
	v_add_u32_e32 v238, 0xa00, v97
	v_min_i32_e32 v238, s52, v238
	v_ashrrev_i32_e32 v239, 31, v238
	v_lshl_add_u64 v[238:239], v[238:239], 4, s[26:27]
	v_add_u32_e32 v240, 0xc00, v97
	v_min_i32_e32 v240, s52, v240
	v_ashrrev_i32_e32 v241, 31, v240
	v_lshl_add_u64 v[240:241], v[240:241], 4, s[26:27]
	v_add_u32_e32 v242, 0xe00, v97
	v_min_i32_e32 v242, s52, v242
	v_ashrrev_i32_e32 v243, 31, v242
	v_lshl_add_u64 v[242:243], v[242:243], 4, s[26:27]
	global_load_dwordx4 v[214:217], v[236:237], off
	global_load_dwordx4 v[218:221], v[238:239], off
	global_load_dwordx4 v[224:227], v[240:241], off
	global_load_dwordx4 v[232:235], v[242:243], off
	v_cmp_gt_i32_e32 vcc, s52, v97
	s_nop 0
	v_cndmask_b32_e32 v120, 1, v2, vcc
	v_bfrev_b32_e32 v121, v120
	v_lshrrev_b32_e32 v121, s49, v121
	v_sub_u32_e32 v121, s7, v121
	v_and_b32_e32 v121, s8, v121
	v_bfrev_b32_e32 v121, v121
	v_lshrrev_b32_e32 v122, s49, v121
	v_ashrrev_i32_e32 v121, 5, v120
	v_lshlrev_b32_e32 v120, 3, v120
	v_lshlrev_b32_e32 v121, 3, v121
	v_add3_u32 v130, 0, v120, v121
	v_lshlrev_b32_e32 v123, 3, v122
	v_lshrrev_b32_e32 v122, 2, v122
	ds_read_b64 v[120:121], v130
	v_and_b32_e32 v122, 0x3ffffff8, v122
	v_add3_u32 v131, 0, v123, v122
	ds_read_b64 v[122:123], v131
	v_cmp_ge_i32_e32 vcc, s52, v111
	s_waitcnt lgkmcnt(1)
	v_pk_mul_f32 v[124:125], v[120:121], v[116:117] op_sel:[1,1] op_sel_hi:[1,0]
	s_nop 0
	v_pk_fma_f32 v[126:127], v[120:121], v[116:117], v[124:125] neg_lo:[0,0,1] neg_hi:[0,0,1]
	v_pk_fma_f32 v[124:125], v[120:121], v[116:117], v[124:125] op_sel_hi:[0,1,1]
	v_mov_b32_e32 v127, v125
	s_waitcnt lgkmcnt(0)
	v_pk_mul_f32 v[124:125], v[118:119], v[122:123] op_sel:[1,1] op_sel_hi:[0,1]
	v_pk_fma_f32 v[128:129], v[118:119], v[122:123], v[124:125]
	v_pk_fma_f32 v[124:125], v[118:119], v[122:123], v[124:125] op_sel_hi:[1,0,1] neg_lo:[0,0,1] neg_hi:[0,0,1]
	s_nop 0
	v_mov_b32_e32 v129, v125
	v_pk_add_f32 v[124:125], v[126:127], v[128:129]
	v_pk_mul_f32 v[126:127], v[116:117], v[122:123] op_sel:[1,1] op_sel_hi:[1,0]
	s_nop 0
	v_pk_fma_f32 v[128:129], v[116:117], v[122:123], v[126:127]
	v_pk_fma_f32 v[116:117], v[116:117], v[122:123], v[126:127] op_sel_hi:[0,1,1] neg_lo:[0,0,1] neg_hi:[0,0,1]
	v_mov_b32_e32 v129, v117
	v_pk_add_f32 v[116:117], v[120:121], 0 neg_lo:[1,1] neg_hi:[1,1]
	v_mov_b32_e32 v122, v119
	v_mov_b32_e32 v116, v120
	v_pk_mul_f32 v[120:121], v[120:121], v[122:123] op_sel:[1,0] op_sel_hi:[0,0]
	v_pk_fma_f32 v[116:117], v[118:119], v[116:117], v[120:121] op_sel_hi:[0,1,1] neg_lo:[0,0,1] neg_hi:[0,0,1]
	v_pk_add_f32 v[116:117], v[116:117], v[128:129]
	ds_write_b64 v131, v[116:117]
	ds_write_b64 v130, v[124:125]
	s_and_saveexec_b64 s[38:39], vcc
	s_cbranch_execnz .LBB0_1461
	s_or_b64 exec, exec, s[38:39]
	v_cmp_ge_i32_e32 vcc, s52, v109
	s_and_saveexec_b64 s[38:39], vcc
	s_cbranch_execnz .LBB0_1462

.LBB0_1519:
	s_mov_b64 s[16:17], exec
	v_readlane_b32 s4, v255, 1
	v_readlane_b32 s5, v255, 2
	s_and_b64 s[4:5], s[16:17], s[4:5]
	s_mov_b64 exec, s[4:5]
	s_cbranch_execz .LBB0_1528
	v_readlane_b32 s4, v251, 62
	s_bitset1_b32 s4, 8
	s_mul_i32 s4, s43, s4
	s_lshl_b32 s4, s4, 4
	s_add_u32 s26, s63, s4
	s_addc_u32 s27, s78, 0
	s_mov_b64 s[34:35], 0
	v_mov_b32_e32 v2, v59
	v_mov_b32_e32 v236, v2
	v_min_i32_e32 v236, s52, v236
	v_ashrrev_i32_e32 v237, 31, v236
	v_lshl_add_u64 v[236:237], v[236:237], 4, s[26:27]
	v_add_u32_e32 v238, 0x200, v2
	v_min_i32_e32 v238, s52, v238
	v_ashrrev_i32_e32 v239, 31, v238
	v_lshl_add_u64 v[238:239], v[238:239], 4, s[26:27]
	v_add_u32_e32 v240, 0x400, v2
	v_min_i32_e32 v240, s52, v240
	v_ashrrev_i32_e32 v241, 31, v240
	v_lshl_add_u64 v[240:241], v[240:241], 4, s[26:27]
	v_add_u32_e32 v242, 0x600, v2
	v_min_i32_e32 v242, s52, v242
	v_ashrrev_i32_e32 v243, 31, v242
	v_lshl_add_u64 v[242:243], v[242:243], 4, s[26:27]
	global_load_dwordx4 v[214:217], v[236:237], off
	global_load_dwordx4 v[218:221], v[238:239], off
	global_load_dwordx4 v[224:227], v[240:241], off
	global_load_dwordx4 v[232:235], v[242:243], off
	s_branch .LBB0_1522

.LBB0_1522:
	v_add_u32_e32 v34, 0x200, v2
	v_add_u32_e32 v33, 0x400, v2
	v_add_u32_e32 v32, 0x600, v2
	s_waitcnt vmcnt(0)
	v_mov_b64_e32 v[38:39], v[214:215]
	v_mov_b64_e32 v[40:41], v[216:217]
	v_mov_b64_e32 v[28:29], v[218:219]
	v_mov_b64_e32 v[30:31], v[220:221]
	v_mov_b64_e32 v[24:25], v[224:225]
	v_mov_b64_e32 v[26:27], v[226:227]
	v_mov_b64_e32 v[20:21], v[232:233]
	v_mov_b64_e32 v[22:23], v[234:235]
	v_add_u32_e32 v236, 0x800, v2
	v_min_i32_e32 v236, s52, v236
	v_ashrrev_i32_e32 v237, 31, v236
	v_lshl_add_u64 v[236:237], v[236:237], 4, s[26:27]
	v_add_u32_e32 v238, 0xa00, v2
	v_min_i32_e32 v238, s52, v238
	v_ashrrev_i32_e32 v239, 31, v238
	v_lshl_add_u64 v[238:239], v[238:239], 4, s[26:27]
	v_add_u32_e32 v240, 0xc00, v2
	v_min_i32_e32 v240, s52, v240
	v_ashrrev_i32_e32 v241, 31, v240
	v_lshl_add_u64 v[240:241], v[240:241], 4, s[26:27]
	v_add_u32_e32 v242, 0xe00, v2
	v_min_i32_e32 v242, s52, v242
	v_ashrrev_i32_e32 v243, 31, v242
	v_lshl_add_u64 v[242:243], v[242:243], 4, s[26:27]
	global_load_dwordx4 v[214:217], v[236:237], off
	global_load_dwordx4 v[218:221], v[238:239], off
	global_load_dwordx4 v[224:227], v[240:241], off
	global_load_dwordx4 v[232:235], v[242:243], off
	v_cmp_gt_i32_e32 vcc, s52, v2
	s_nop 0
	v_cndmask_b32_e32 v35, 1, v158, vcc
	v_bfrev_b32_e32 v42, v35
	v_lshrrev_b32_e32 v42, s49, v42
	v_sub_u32_e32 v42, s7, v42
	v_and_b32_e32 v42, s8, v42
	v_bfrev_b32_e32 v42, v42
	v_lshrrev_b32_e32 v44, s49, v42
	v_ashrrev_i32_e32 v42, 5, v35
	v_lshlrev_b32_e32 v35, 3, v35
	v_lshlrev_b32_e32 v42, 3, v42
	v_add3_u32 v35, 0, v35, v42
	v_lshlrev_b32_e32 v45, 3, v44
	v_lshrrev_b32_e32 v44, 2, v44
	ds_read_b64 v[42:43], v35
	v_and_b32_e32 v44, 0x3ffffff8, v44
	v_add3_u32 v100, 0, v45, v44
	ds_read_b64 v[44:45], v100
	v_cmp_ge_i32_e32 vcc, s52, v34
	s_waitcnt lgkmcnt(0)
	v_pk_mul_f32 v[46:47], v[42:43], v[38:39] op_sel:[1,1] op_sel_hi:[1,0]
	s_nop 0
	v_pk_fma_f32 v[96:97], v[42:43], v[38:39], v[46:47] neg_lo:[0,0,1] neg_hi:[0,0,1]
	v_pk_fma_f32 v[46:47], v[42:43], v[38:39], v[46:47] op_sel_hi:[0,1,1]
	v_mov_b32_e32 v97, v47
	v_pk_mul_f32 v[46:47], v[40:41], v[44:45] op_sel:[1,1] op_sel_hi:[0,1]
	v_pk_fma_f32 v[98:99], v[40:41], v[44:45], v[46:47]
	v_pk_fma_f32 v[46:47], v[40:41], v[44:45], v[46:47] op_sel_hi:[1,0,1] neg_lo:[0,0,1] neg_hi:[0,0,1]
	s_nop 0
	v_mov_b32_e32 v99, v47
	v_pk_add_f32 v[46:47], v[96:97], v[98:99]
	v_pk_mul_f32 v[96:97], v[38:39], v[44:45] op_sel:[1,1] op_sel_hi:[1,0]
	s_nop 0
	v_pk_fma_f32 v[98:99], v[38:39], v[44:45], v[96:97]
	v_pk_fma_f32 v[38:39], v[38:39], v[44:45], v[96:97] op_sel_hi:[0,1,1] neg_lo:[0,0,1] neg_hi:[0,0,1]
	v_mov_b32_e32 v99, v39
	v_pk_add_f32 v[38:39], v[42:43], 0 neg_lo:[1,1] neg_hi:[1,1]
	v_mov_b32_e32 v44, v41
	v_mov_b32_e32 v38, v42
	v_pk_mul_f32 v[42:43], v[42:43], v[44:45] op_sel:[1,0] op_sel_hi:[0,0]
	v_pk_fma_f32 v[38:39], v[40:41], v[38:39], v[42:43] op_sel_hi:[0,1,1] neg_lo:[0,0,1] neg_hi:[0,0,1]
	v_pk_add_f32 v[38:39], v[38:39], v[98:99]
	ds_write_b64 v100, v[38:39]
	ds_write_b64 v35, v[46:47]
	s_and_saveexec_b64 s[38:39], vcc
	s_cbranch_execnz .LBB0_1525
	s_or_b64 exec, exec, s[38:39]
	v_cmp_ge_i32_e32 vcc, s52, v33
	s_and_saveexec_b64 s[38:39], vcc
	s_cbranch_execnz .LBB0_1526

.LBB0_2615:
	s_or_b64 exec, exec, s[16:17]
	v_readlane_b32 s8, v251, 20
	s_waitcnt lgkmcnt(0)
	s_barrier
	v_mov_b32_e32 v2, s8
	ds_read_b32 v2, v2
	s_mov_b64 s[14:15], -1
	s_waitcnt lgkmcnt(0)
	v_cmp_lt_i32_e32 vcc, 0xa7, v2
	v_readfirstlane_b32 s8, v2
	s_cbranch_vccnz .LBB0_2610
	v_mov_b32_e32 v72, v0
	s_movk_i32 s11, 0xd0
	s_cmp_lt_u32 s8, 32
	s_cselect_b32 s11, 0x1e0, s11
	s_add_i32 s8, s8, s11
	s_and_b32 s11, s8, 0xff
	v_readfirstlane_b32 s9, v72
	v_cmp_lt_i32_e32 vcc, 3, v72
	v_and_b32_e32 v6, 1, v72
	s_barrier
	s_and_saveexec_b64 s[14:15], vcc
	s_xor_b64 s[14:15], exec, s[14:15]
	s_lshl_b32 s12, s11, 1
	v_and_b32_e32 v6, 1, v72
	s_or_saveexec_b64 s[16:17], s[14:15]
	s_lshl_b32 s10, s8, 2
	s_and_b32 s10, s10, 0x400
	v_mov_b32_e32 v7, s12
	v_lshlrev_b32_e32 v2, 8, v72
	v_lshl_add_u32 v73, v72, 2, 0
	s_xor_b64 exec, exec, s[16:17]
	s_cbranch_execz .LBB0_2620
	s_load_dwordx2 s[12:13], s[0:1], 0xe0
	v_and_b32_e32 v4, 0xfffffe00, v2
	v_add_u32_e32 v4, s10, v4
	s_lshl_b32 s11, s11, 1
	v_or3_b32 v4, v4, v6, s11
	s_waitcnt lgkmcnt(0)
	s_add_u32 s12, s12, s34
	v_ashrrev_i32_e32 v5, 31, v4
	s_addc_u32 s13, s13, s35
	v_lshl_add_u64 v[4:5], v[4:5], 2, s[12:13]
	flat_load_dword v4, v[4:5]
	v_add_u32_e32 v5, 0x21400, v73
	v_mov_b32_e32 v7, s11
	s_waitcnt vmcnt(0) lgkmcnt(0)
	ds_write_b32 v5, v4
